# attention item setup: serial 48/32-load gmax chain replaced by one load per lane + DPP max reduction
# speedup vs baseline: 1.1772x; 1.0199x over previous
; DEV int tid_() { int t = threadIdx.x; asm volatile("" : "+v"(t)); return t; }
; template <int DQK> ...
;     ...
;   int tid = tid_(), lane = tid & 63, wave = tid >> 6;
;   int hh = lane >> 5;
;   int qi = wave * 32 + (lane & 31);
;   int qrow = qrow0 + qi;
;   bf16x8 qf[NKS];
; #pragma unroll
;   for (int ks = 0; ks < NKS; ks++) qf[ks] = *(const bf16x8*)(Qp + (size_t)qi * ldq + ks * 16 + hh * 8);
;   f32x16 o[2];
; #pragma unroll
;   for (int db = 0; db < 2; db++)
; #pragma unroll
;     for (int r = 0; r < 16; r++) o[db][r] = 0.f;
;   const float scale2 = scale * 1.4426950408889634f;
;   float gmax = 0.f;
;   for (int dd = 0; dd < DQK; dd++) gmax = fmaxf(gmax, fabsf(kgain[dd]));
; __device__ void attn_dispatch(PRef p, int l, int it, AttnSm* sm) {
;     ...
;     sink = p.c_sink[l * 8 + h];
;     int kvh = h >> 2;
;     attn_item<64>(p.ZC + (size_t)row0 * 768 + h * 64, 768, p.ZC + 512 + kvh * 64, 768, nullptr, 0, p.ZC + 640 + kvh * 64, 768,
.LBB0_649:
	s_and_b32 s35, s0, 7
	s_or_b32 s0, s35, s46
	s_ashr_i32 s1, s0, 31
	s_lshl_b64 s[0:1], s[0:1], 2
	s_add_u32 s0, s22, s0
	s_addc_u32 s1, s23, s1
	global_load_dword v0, v3, s[0:1]
	s_mul_i32 s1, s34, 0x600
	s_mul_hi_i32 s0, s34, 0x600
	s_add_u32 s1, s26, s1
	s_addc_u32 s4, s27, s0
	s_lshl_b32 s0, s35, 7
	s_add_u32 s0, s1, s0
	s_waitcnt vmcnt(8)
	v_mov_b32_e32 v5, v196
	s_addc_u32 s1, s4, 0
	v_mov_b64_e32 v[6:7], s[0:1]
	v_ashrrev_i32_e32 v2, 1, v5
	v_bfe_u32 v1, v5, 5, 1
	v_bfi_b32 v4, s62, v2, v5
	v_mad_i64_i32 v[150:151], s[0:1], v4, s65, v[6:7]
	v_lshlrev_b32_e32 v2, 4, v1
	v_lshl_add_u64 v[6:7], v[150:151], 0, v[2:3]
	global_load_dwordx4 v[100:103], v[6:7], off
	global_load_dwordx4 v[104:107], v[6:7], off offset:32
	global_load_dwordx4 v[108:111], v[6:7], off offset:64
	global_load_dwordx4 v[112:115], v[6:7], off offset:96
	v_and_b32_e32 v6, 31, v5
	v_and_b32_e32 v8, 63, v196
	v_lshlrev_b32_e32 v8, 2, v8
	global_load_dword v7, v8, s[18:19]
	s_waitcnt vmcnt(0)
	v_max_f32_e64 v7, |v7|, |v7|
	s_nop 1
	v_max_f32_dpp v7, v7, v7 quad_perm:[1,0,3,2] row_mask:0xf bank_mask:0xf
	s_nop 1
	v_max_f32_dpp v7, v7, v7 quad_perm:[2,3,0,1] row_mask:0xf bank_mask:0xf
	s_nop 1
	v_max_f32_dpp v7, v7, v7 row_half_mirror row_mask:0xf bank_mask:0xf
	s_nop 1
	v_max_f32_dpp v7, v7, v7 row_mirror row_mask:0xf bank_mask:0xf
	s_nop 1
	v_max_f32_dpp v7, v7, v7 row_bcast:15 row_mask:0xa bank_mask:0xf
	s_nop 1
	v_max_f32_dpp v7, v7, v7 row_bcast:31 row_mask:0xc bank_mask:0xf
	s_nop 1
	v_readlane_b32 s98, v7, 63
	s_nop 3
	v_mov_b32_e32 v7, s98

; DEV int tid_() { int t = threadIdx.x; asm volatile("" : "+v"(t)); return t; }
; template <int DQK> ...
;     ...
;   int tid = tid_(), lane = tid & 63, wave = tid >> 6;
;   int hh = lane >> 5;
;   int qi = wave * 32 + (lane & 31);
;   int qrow = qrow0 + qi;
;   bf16x8 qf[NKS];
; #pragma unroll
;   for (int ks = 0; ks < NKS; ks++) qf[ks] = *(const bf16x8*)(Qp + (size_t)qi * ldq + ks * 16 + hh * 8);
;   f32x16 o[2];
; #pragma unroll
;   for (int db = 0; db < 2; db++)
; #pragma unroll
;     for (int r = 0; r < 16; r++) o[db][r] = 0.f;
;   const float scale2 = scale * 1.4426950408889634f;
;   float gmax = 0.f;
;   for (int dd = 0; dd < DQK; dd++) gmax = fmaxf(gmax, fabsf(kgain[dd]));
; __device__ void attn_dispatch(PRef p, int l, int it, AttnSm* sm) {
;     ...
;     attn_item<96>(p.Q + (size_t)row0 * 768 + h * 96, 768, p.KV + h * 128, 1024, p.KR + h * 32, 256, p.KV + h * 128 + 64,
;                   1024, b * TPB, ktiles, 0, 0, row0, false, 0.10206207261596575f, false, 0.f,
;                   p.ZB + (size_t)row0 * 512 + h * 64, 512, sm, p.b_kn_g + l * 96);
.LBB0_669:
	s_and_b32 s48, s0, 7
	s_ashr_i32 s41, s40, 31
	s_mul_i32 s1, s40, 0x600
	v_readlane_b32 s4, v245, 4
	s_mul_hi_i32 s0, s40, 0x600
	v_readlane_b32 s5, v245, 5
	s_add_u32 s1, s4, s1
	s_addc_u32 s4, s5, s0
	s_mul_i32 s0, s48, 0xc0
	s_add_u32 s0, s1, s0
	s_waitcnt vmcnt(0)
	v_mov_b32_e32 v34, v196
	s_addc_u32 s1, s4, 0
	v_mov_b64_e32 v[4:5], s[0:1]
	v_ashrrev_i32_e32 v0, 1, v34
	v_bfe_u32 v35, v34, 5, 1
	v_bfi_b32 v0, s62, v0, v34
	v_mad_i64_i32 v[6:7], s[0:1], v0, s65, v[4:5]
	v_lshlrev_b32_e32 v4, 4, v35
	v_mov_b32_e32 v5, v3
	v_lshl_add_u64 v[6:7], v[6:7], 0, v[4:5]
	global_load_dwordx4 v[100:103], v[6:7], off
	global_load_dwordx4 v[104:107], v[6:7], off offset:32
	global_load_dwordx4 v[108:111], v[6:7], off offset:64
	global_load_dwordx4 v[112:115], v[6:7], off offset:96
	global_load_dwordx4 v[116:119], v[6:7], off offset:128
	global_load_dwordx4 v[120:123], v[6:7], off offset:160
	v_and_b32_e32 v5, 31, v34
	v_ashrrev_i32_e32 v1, 31, v0
	v_and_b32_e32 v2, 63, v196
	v_min_u32_e32 v6, 31, v2
	v_lshlrev_b32_e32 v2, 2, v2
	v_lshlrev_b32_e32 v6, 2, v6
	global_load_dword v36, v2, s[20:21]
	global_load_dword v6, v6, s[20:21] offset:256
	s_waitcnt vmcnt(0)
	v_max_f32_e64 v36, |v36|, |v6|
	s_nop 1
	v_max_f32_dpp v36, v36, v36 quad_perm:[1,0,3,2] row_mask:0xf bank_mask:0xf
	s_nop 1
	v_max_f32_dpp v36, v36, v36 quad_perm:[2,3,0,1] row_mask:0xf bank_mask:0xf
	s_nop 1
	v_max_f32_dpp v36, v36, v36 row_half_mirror row_mask:0xf bank_mask:0xf
	s_nop 1
	v_max_f32_dpp v36, v36, v36 row_mirror row_mask:0xf bank_mask:0xf
	s_nop 1
	v_max_f32_dpp v36, v36, v36 row_bcast:15 row_mask:0xa bank_mask:0xf
	s_nop 1
	v_max_f32_dpp v36, v36, v36 row_bcast:31 row_mask:0xc bank_mask:0xf
	s_nop 1
	v_readlane_b32 s98, v36, 63
	s_nop 3
	v_mov_b32_e32 v36, s98

; __global__ void __launch_bounds__(256, 2) fwd_megakernel(Params p) {
	.amdhsa_kernel _Z14fwd_megakernel6Params
		.amdhsa_group_segment_fixed_size 63520
		.amdhsa_private_segment_fixed_size 0
		.amdhsa_kernarg_size 664
		.amdhsa_user_sgpr_count 2
		.amdhsa_user_sgpr_dispatch_ptr 0
		.amdhsa_user_sgpr_queue_ptr 0
		.amdhsa_user_sgpr_kernarg_segment_ptr 1
		.amdhsa_user_sgpr_dispatch_id 0
		.amdhsa_user_sgpr_kernarg_preload_length 0
		.amdhsa_user_sgpr_kernarg_preload_offset 0
		.amdhsa_user_sgpr_private_segment_size 0
		.amdhsa_uses_dynamic_stack 0
		.amdhsa_enable_private_segment 0
		.amdhsa_system_sgpr_workgroup_id_x 1
		.amdhsa_system_sgpr_workgroup_id_y 0
		.amdhsa_system_sgpr_workgroup_id_z 0
		.amdhsa_system_sgpr_workgroup_info 0
		.amdhsa_system_vgpr_workitem_id 2
		.amdhsa_next_free_vgpr 256
		.amdhsa_next_free_sgpr 102
		.amdhsa_accum_offset 256
		.amdhsa_reserve_vcc 1
		.amdhsa_float_round_mode_32 0
		.amdhsa_float_round_mode_16_64 0
		.amdhsa_float_denorm_mode_32 3
		.amdhsa_float_denorm_mode_16_64 3
		.amdhsa_dx10_clamp 1
		.amdhsa_ieee_mode 1
		.amdhsa_fp16_overflow 0
		.amdhsa_tg_split 0
		.amdhsa_exception_fp_ieee_invalid_op 0
		.amdhsa_exception_fp_denorm_src 0
		.amdhsa_exception_fp_ieee_div_zero 0
		.amdhsa_exception_fp_ieee_overflow 0
		.amdhsa_exception_fp_ieee_underflow 0
		.amdhsa_exception_fp_ieee_inexact 0
		.amdhsa_exception_int_div_zero 0
	.end_amdhsa_kernel

; __global__ void __launch_bounds__(256, 2) fwd_megakernel(Params p) {
;   cg::grid_group grid = cg::this_grid();
;   __shared__ __attribute__((aligned(16))) unsigned char smem[SMEM_BYTES];
amdhsa.kernels:
  - .agpr_count:     0
    .args:
      - .offset:         0
        .size:           408
        .value_kind:     by_value
      - .offset:         408
        .size:           4
        .value_kind:     hidden_block_count_x
      - .offset:         412
        .size:           4
        .value_kind:     hidden_block_count_y
      - .offset:         416
        .size:           4
        .value_kind:     hidden_block_count_z
      - .offset:         420
        .size:           2
        .value_kind:     hidden_group_size_x
      - .offset:         422
        .size:           2
        .value_kind:     hidden_group_size_y
      - .offset:         424
        .size:           2
        .value_kind:     hidden_group_size_z
      - .offset:         426
        .size:           2
        .value_kind:     hidden_remainder_x
      - .offset:         428
        .size:           2
        .value_kind:     hidden_remainder_y
      - .offset:         430
        .size:           2
        .value_kind:     hidden_remainder_z
      - .offset:         448
        .size:           8
        .value_kind:     hidden_global_offset_x
      - .offset:         456
        .size:           8
        .value_kind:     hidden_global_offset_y
      - .offset:         464
        .size:           8
        .value_kind:     hidden_global_offset_z
      - .offset:         472
        .size:           2
        .value_kind:     hidden_grid_dims
      - .offset:         496
        .size:           8
        .value_kind:     hidden_multigrid_sync_arg
    .group_segment_fixed_size: 63520
    .kernarg_segment_align: 8
    .kernarg_segment_size: 664
    .language:       OpenCL C
    .language_version:
      - 2
      - 0
    .max_flat_workgroup_size: 256
    .name:           _Z14fwd_megakernel6Params
    .private_segment_fixed_size: 0
    .sgpr_count:     108
    .sgpr_spill_count: 125
    .symbol:         _Z14fwd_megakernel6Params.kd
    .uniform_work_group_size: 1
    .uses_dynamic_stack: false
    .vgpr_count:     256
    .vgpr_spill_count: 0
    .wavefront_size: 64
